# attention loop 2x unrolled, V tiles double-buffered in registers, per-MFMA LDS waits
# baseline (speedup 1.0000x reference)
.LBB0_1338:
	v_mov_b32_e32 v54, v191
	s_lshl_b32 s97, s4, 8
	s_add_i32 s97, s97, s79
	v_and_b32_e32 v48, 31, v54
	v_or_b32_e32 v0, s97, v48
	v_ashrrev_i32_e32 v50, 3, v54
	v_and_b32_e32 v56, 7, v54
	v_bfe_u32 v49, v54, 5, 1
	v_add_u32_e32 v0, s91, v0
	s_movk_i32 s0, 0xc00
	v_ashrrev_i32_e32 v51, 4, v54
	v_and_b32_e32 v55, 15, v54
	v_add_u32_e32 v9, s91, v50
	v_lshlrev_b32_e32 v52, 3, v56
	v_ashrrev_i32_e32 v1, 31, v0
	v_mad_i64_i32 v[2:3], s[0:1], v0, s0, v[182:183]
	v_lshlrev_b32_e32 v180, 4, v49
	v_add_lshl_u32 v8, v51, s91, 10
	v_lshlrev_b32_e32 v53, 3, v55
	v_lshl_or_b32 v10, v9, 6, v52
	v_add_lshl_u32 v9, v50, s92, 15
	v_lshl_add_u64 v[24:25], v[2:3], 0, v[180:181]
	v_lshlrev_b64 v[0:1], 7, v[0:1]
	v_or3_b32 v8, v8, v53, s92
	v_or3_b32 v12, v9, s91, v52
	v_add_lshl_u32 v234, v50, s92, 11
	v_add_u32_e32 v12, v12, v234
	v_mov_b32_e32 v9, v181
	global_load_dwordx4 v[96:99], v[24:25], off
	global_load_dwordx4 v[100:103], v[24:25], off offset:32
	global_load_dwordx4 v[104:107], v[24:25], off offset:64
	global_load_dwordx4 v[108:111], v[24:25], off offset:96
	global_load_dwordx4 v[112:115], v[24:25], off offset:128
	global_load_dwordx4 v[116:119], v[24:25], off offset:160
	global_load_dwordx4 v[120:123], v[24:25], off offset:192
	global_load_dwordx4 v[124:127], v[24:25], off offset:224
	v_lshl_add_u64 v[2:3], s[62:63], 0, v[0:1]
	v_lshlrev_b32_e32 v4, 5, v49
	v_mov_b32_e32 v5, v181
	v_lshl_add_u64 v[14:15], v[8:9], 1, s[64:65]
	v_add_u32_e32 v8, 0x8000, v8
	v_lshl_add_u64 v[28:29], v[2:3], 0, v[4:5]
	v_lshl_add_u64 v[0:1], s[66:67], 0, v[0:1]
	v_lshl_add_u64 v[8:9], v[8:9], 1, s[64:65]
	v_mov_b32_e32 v11, v181
	v_lshl_add_u64 v[44:45], v[0:1], 0, v[4:5]
	global_load_dwordx4 v[0:3], v[28:29], off offset:16
	global_load_dwordx4 v[4:7], v[28:29], off
	global_load_dwordx4 v[128:131], v[14:15], off
	global_load_dwordx4 v[132:135], v[8:9], off
	v_lshl_add_u64 v[8:9], v[10:11], 1, s[60:61]
	v_mov_b32_e32 v13, v181
	v_lshl_add_u64 v[10:11], v[12:13], 1, s[68:69]
	global_load_dwordx4 v[136:139], v[8:9], off
	global_load_dwordx4 v[140:143], v[10:11], off
	v_add_u32_e32 v8, 0x220000, v12
	v_mov_b32_e32 v9, v181
	v_lshl_add_u64 v[8:9], v[8:9], 1, s[68:69]
	global_load_dwordx4 v[144:147], v[8:9], off
	s_nop 0
	global_load_dwordx4 v[8:11], v[44:45], off offset:16
	global_load_dwordx4 v[20:23], v[44:45], off
	global_load_dwordx4 v[12:15], v[24:25], off offset:256
	global_load_dwordx4 v[32:35], v[24:25], off offset:288
	global_load_dwordx4 v[16:19], v[24:25], off offset:320
	global_load_dwordx4 v[36:39], v[24:25], off offset:352
	s_nop 0
	global_load_dwordx4 v[24:27], v[28:29], off offset:80
	global_load_dwordx4 v[40:43], v[28:29], off offset:64
	s_nop 0
	global_load_dwordx4 v[28:31], v[44:45], off offset:80
	s_nop 0
	global_load_dwordx4 v[44:47], v[44:45], off offset:64
	v_lshlrev_b32_e32 v57, 3, v54
	v_mul_lo_u32 v58, v51, s82
	v_lshlrev_b32_e32 v54, 4, v56
	v_mul_lo_u32 v56, v50, s83
	v_lshl_add_u32 v194, v55, 4, v58
	v_and_b32_e32 v55, 0x60, v54
	v_and_b32_e32 v57, 8, v57
	v_mad_u64_u32 v[184:185], s[0:1], v50, s82, v[54:55]
	v_add_u32_e32 v54, 0, v56
	v_add3_u32 v185, v54, v57, v55
	v_add_u32_e32 v56, 0, v194
	v_add_u32_e32 v54, 0xc800, v185
	v_add_u32_e32 v58, 0, v184
	v_add_u32_e32 v55, 0xe800, v185
	s_cmp_lt_i32 s4, 0
	s_mov_b32 s52, 0
	s_waitcnt vmcnt(0)
	ds_write_b128 v56, v[128:131]
	ds_write_b128 v56, v[132:135] offset:12800
	ds_write_b128 v58, v[136:139] offset:256
	ds_write2_b64 v54, v[140:141], v[142:143] offset1:2
	ds_write2_b64 v55, v[144:145], v[146:147] offset0:128 offset1:130
	v_mad_u32_u24 v54, v48, s83, 0
	v_add_u32_e32 v195, v54, v180
	v_add_u32_e32 v173, 0xc800, v195
	s_waitcnt lgkmcnt(0)
	s_barrier
	s_cbranch_scc1 .LBB0_1331
	v_lshlrev_b32_e32 v55, 8, v48
	v_add3_u32 v196, v54, v55, v180
	v_and_b32_e32 v55, 0xffff0000, v36
	v_lshlrev_b32_e32 v54, 16, v36
	v_and_b32_e32 v57, 0xffff0000, v32
	v_lshlrev_b32_e32 v56, 16, v32
	v_pk_mul_f32 v[58:59], v[44:45], v[56:57]
	v_pk_mul_f32 v[44:45], v[44:45], v[54:55]
	v_pk_fma_f32 v[58:59], v[40:41], v[54:55], v[58:59]
	v_pk_fma_f32 v[40:41], v[40:41], v[56:57], v[44:45] neg_lo:[0,0,1] neg_hi:[0,0,1]
	v_lshlrev_b32_e32 v36, 16, v33
	v_cvt_pk_bf16_f32 v152, v40, v41
	v_and_b32_e32 v41, 0xffff0000, v37
	v_lshlrev_b32_e32 v40, 16, v37
	v_and_b32_e32 v37, 0xffff0000, v33
	v_pk_mul_f32 v[32:33], v[46:47], v[36:37]
	s_lshl_b32 s53, s4, 2
	v_pk_fma_f32 v[32:33], v[42:43], v[40:41], v[32:33]
	v_mov_b32_e32 v200, 0
	v_cvt_pk_bf16_f32 v149, v32, v33
	v_pk_mul_f32 v[32:33], v[46:47], v[40:41]
	s_add_i32 s53, s53, 4
	v_pk_fma_f32 v[32:33], v[42:43], v[36:37], v[32:33] neg_lo:[0,0,1] neg_hi:[0,0,1]
	v_and_b32_e32 v37, 0xffff0000, v34
	v_cvt_pk_bf16_f32 v153, v32, v33
	v_and_b32_e32 v33, 0xffff0000, v38
	v_lshlrev_b32_e32 v32, 16, v38
	v_lshlrev_b32_e32 v36, 16, v34
	v_pk_mul_f32 v[40:41], v[28:29], v[36:37]
	v_pk_mul_f32 v[28:29], v[28:29], v[32:33]
	v_pk_fma_f32 v[40:41], v[24:25], v[32:33], v[40:41]
	v_pk_fma_f32 v[24:25], v[24:25], v[36:37], v[28:29] neg_lo:[0,0,1] neg_hi:[0,0,1]
	v_and_b32_e32 v29, 0xffff0000, v35
	v_lshlrev_b32_e32 v28, 16, v35
	v_cvt_pk_bf16_f32 v154, v24, v25
	v_and_b32_e32 v25, 0xffff0000, v39
	v_lshlrev_b32_e32 v24, 16, v39
	v_pk_mul_f32 v[32:33], v[30:31], v[28:29]
	v_cvt_pk_bf16_f32 v148, v58, v59
	v_pk_fma_f32 v[32:33], v[26:27], v[24:25], v[32:33]
	v_pk_mul_f32 v[24:25], v[30:31], v[24:25]
	v_cvt_pk_bf16_f32 v150, v40, v41
	v_pk_fma_f32 v[24:25], v[26:27], v[28:29], v[24:25] neg_lo:[0,0,1] neg_hi:[0,0,1]
	v_and_b32_e32 v27, 0xffff0000, v12
	v_cvt_pk_bf16_f32 v155, v24, v25
	v_and_b32_e32 v25, 0xffff0000, v16
	v_lshlrev_b32_e32 v24, 16, v16
	v_lshlrev_b32_e32 v26, 16, v12
	v_pk_mul_f32 v[28:29], v[20:21], v[26:27]
	v_pk_mul_f32 v[20:21], v[20:21], v[24:25]
	v_pk_fma_f32 v[28:29], v[4:5], v[24:25], v[28:29]
	v_pk_fma_f32 v[4:5], v[4:5], v[26:27], v[20:21] neg_lo:[0,0,1] neg_hi:[0,0,1]
	v_lshlrev_b32_e32 v16, 16, v13
	v_cvt_pk_bf16_f32 v160, v4, v5
	v_and_b32_e32 v5, 0xffff0000, v17
	v_lshlrev_b32_e32 v4, 16, v17
	v_and_b32_e32 v17, 0xffff0000, v13
	v_pk_mul_f32 v[12:13], v[22:23], v[16:17]
	v_cvt_pk_bf16_f32 v151, v32, v33
	v_pk_fma_f32 v[12:13], v[6:7], v[4:5], v[12:13]
	v_pk_mul_f32 v[4:5], v[22:23], v[4:5]
	v_cvt_pk_bf16_f32 v157, v12, v13
	v_pk_fma_f32 v[4:5], v[6:7], v[16:17], v[4:5] neg_lo:[0,0,1] neg_hi:[0,0,1]
	v_and_b32_e32 v7, 0xffff0000, v14
	v_lshlrev_b32_e32 v6, 16, v14
	v_cvt_pk_bf16_f32 v161, v4, v5
	v_and_b32_e32 v5, 0xffff0000, v18
	v_lshlrev_b32_e32 v4, 16, v18
	v_pk_mul_f32 v[12:13], v[8:9], v[6:7]
	v_cvt_pk_bf16_f32 v156, v28, v29
	v_pk_fma_f32 v[12:13], v[0:1], v[4:5], v[12:13]
	v_pk_mul_f32 v[4:5], v[8:9], v[4:5]
	v_cvt_pk_bf16_f32 v158, v12, v13
	v_pk_fma_f32 v[0:1], v[0:1], v[6:7], v[4:5] neg_lo:[0,0,1] neg_hi:[0,0,1]
	v_and_b32_e32 v5, 0xffff0000, v15
	v_lshlrev_b32_e32 v4, 16, v15
	v_cvt_pk_bf16_f32 v162, v0, v1
	v_and_b32_e32 v1, 0xffff0000, v19
	v_lshlrev_b32_e32 v0, 16, v19
	v_pk_mul_f32 v[6:7], v[10:11], v[4:5]
	v_mov_b32_e32 v199, 0xf149f2ca
	v_pk_fma_f32 v[6:7], v[2:3], v[0:1], v[6:7]
	v_pk_mul_f32 v[0:1], v[10:11], v[0:1]
	v_cvt_pk_bf16_f32 v159, v6, v7
	v_pk_fma_f32 v[0:1], v[2:3], v[4:5], v[0:1] neg_lo:[0,0,1] neg_hi:[0,0,1]
	s_mov_b32 s33, 63
	v_cvt_pk_bf16_f32 v163, v0, v1
	v_lshlrev_b32_e32 v1, 10, v51
	v_lshlrev_b32_e32 v0, 2, v49
	v_add3_u32 v186, s93, v1, v53
	v_add_u32_e32 v1, s97, v48
	v_sub_u32_e32 v197, v1, v0
	v_lshlrev_b32_e32 v0, 6, v50
	v_add3_u32 v188, s94, v0, v52
	v_lshlrev_b32_e32 v0, 15, v50
	v_add3_u32 v198, s95, v0, v52
	v_add_lshl_u32 v234, v50, s92, 11
	v_add_u32_e32 v198, v198, v234
	v_mov_b32_e32 v64, 0
	v_mov_b32_e32 v65, 0
	v_mov_b32_e32 v66, 0
	v_mov_b32_e32 v67, 0
	v_mov_b32_e32 v68, 0
	v_mov_b32_e32 v69, 0
	v_mov_b32_e32 v70, 0
	v_mov_b32_e32 v71, 0
	s_mov_b32 s0, 0
	v_mov_b32_e32 v0, 0
	v_mov_b32_e32 v1, v200
	v_mov_b32_e32 v2, v200
	v_mov_b32_e32 v3, v200
	v_mov_b32_e32 v4, v200
	v_mov_b32_e32 v5, v200
	v_mov_b32_e32 v6, v200
	v_mov_b32_e32 v7, v200
	v_mov_b32_e32 v8, v200
	v_mov_b32_e32 v9, v200
	v_mov_b32_e32 v10, v200
	v_mov_b32_e32 v11, v200
	v_mov_b32_e32 v12, v200
	v_mov_b32_e32 v13, v200
	v_mov_b32_e32 v14, v200
	v_mov_b32_e32 v15, v200
	v_mov_b32_e32 v16, 0
	v_mov_b32_e32 v17, v200
	v_mov_b32_e32 v18, v200
	v_mov_b32_e32 v19, v200
	v_mov_b32_e32 v20, v200
	v_mov_b32_e32 v21, v200
	v_mov_b32_e32 v22, v200
	v_mov_b32_e32 v23, v200
	v_mov_b32_e32 v24, v200
	v_mov_b32_e32 v25, v200
	v_mov_b32_e32 v26, v200
	v_mov_b32_e32 v27, v200
	v_mov_b32_e32 v28, v200
	v_mov_b32_e32 v29, v200
	v_mov_b32_e32 v30, v200
	v_mov_b32_e32 v31, v200
	v_mov_b32_e32 v32, 0
	v_mov_b32_e32 v33, v200
	v_mov_b32_e32 v34, v200
	v_mov_b32_e32 v35, v200
	v_mov_b32_e32 v36, v200
	v_mov_b32_e32 v37, v200
	v_mov_b32_e32 v38, v200
	v_mov_b32_e32 v39, v200
	v_mov_b32_e32 v40, v200
	v_mov_b32_e32 v41, v200
	v_mov_b32_e32 v42, v200
	v_mov_b32_e32 v43, v200
	v_mov_b32_e32 v44, v200
	v_mov_b32_e32 v45, v200
	v_mov_b32_e32 v46, v200
	v_mov_b32_e32 v47, v200
	v_mov_b32_e32 v48, 0
	v_mov_b32_e32 v49, v200
	v_mov_b32_e32 v50, v200
	v_mov_b32_e32 v51, v200
	v_mov_b32_e32 v52, v200
	v_mov_b32_e32 v53, v200
	v_mov_b32_e32 v54, v200
	v_mov_b32_e32 v55, v200
	v_mov_b32_e32 v56, v200
	v_mov_b32_e32 v57, v200
	v_mov_b32_e32 v58, v200
	v_mov_b32_e32 v59, v200
	v_mov_b32_e32 v60, v200
	v_mov_b32_e32 v61, v200
	v_mov_b32_e32 v62, v200
	v_mov_b32_e32 v63, v200
	v_mov_b32_e32 v187, 0
	v_mov_b32_e32 v189, 0
	v_xor_b32_e32 v246, 32, v193
	v_lshlrev_b32_e32 v246, 2, v246
	v_mov_b32_e32 v64, 0xff61b1e6
	v_mov_b32_e32 v65, v64
	v_mov_b32_e32 v66, v64
	v_mov_b32_e32 v67, v64
	v_mov_b32_e32 v68, v64
	v_mov_b32_e32 v69, v64
	v_mov_b32_e32 v70, v64
	v_mov_b32_e32 v71, v64
	v_mov_b32_e32 v72, v64
	v_mov_b32_e32 v73, v64
	v_mov_b32_e32 v74, v64
	v_mov_b32_e32 v75, v64
	v_mov_b32_e32 v76, v64
	v_mov_b32_e32 v77, v64
	v_mov_b32_e32 v78, v64
	v_mov_b32_e32 v79, v64
	v_add_u32_e32 v201, 0xffff8000, v186
	v_lshlrev_b32_e32 v201, 1, v201
	v_lshlrev_b32_e32 v230, 1, v186
	v_lshlrev_b32_e32 v231, 1, v188
	v_add_u32_e32 v232, 64, v198
	v_lshlrev_b32_e32 v232, 1, v232
	v_add_u32_e32 v233, 0x440000, v232
	s_mov_b64 s[20:21], s[64:65]
	s_mov_b64 s[22:23], s[60:61]
	s_mov_b64 s[24:25], s[68:69]
	global_load_dwordx4 v[236:239], v232, s[24:25]
	global_load_dwordx4 v[240:243], v233, s[24:25]
	global_load_dwordx4 v[128:131], v201, s[20:21]
	global_load_dwordx4 v[132:135], v230, s[20:21]
	global_load_dwordx4 v[136:139], v231, s[22:23]
	s_add_u32 s24, s24, 0x80
	s_addc_u32 s25, s25, 0
	global_load_dwordx4 v[140:143], v232, s[24:25]
	global_load_dwordx4 v[144:147], v233, s[24:25]
.LBB0_1340:
	s_add_i32 s54, s0, 1
	v_mov_b32_e32 v174, v196
	s_mul_i32 s4, s52, 0x4800
	v_add_u32_e32 v234, s4, v195
	ds_read_b128 v[202:205], v174 offset:0
	ds_read_b128 v[206:209], v174 offset:32
	ds_read_b128 v[210:213], v174 offset:64
	ds_read_b128 v[214:217], v174 offset:96
	ds_read_b128 v[218:221], v174 offset:128
	ds_read_b128 v[222:225], v174 offset:160
	v_fma_f32 v64, v64, s84, -v199
	v_exp_f32_e32 v64, v64
	v_fma_f32 v65, v65, s84, -v199
	v_exp_f32_e32 v65, v65
	v_add_f32_e32 v200, v200, v64
	v_fma_f32 v66, v66, s84, -v199
	v_exp_f32_e32 v66, v66
	v_add_f32_e32 v200, v200, v65
	s_waitcnt lgkmcnt(5)
	v_mfma_f32_32x32x16_bf16 v[80:95], v[202:205], v[96:99], 0
	ds_read_b128 v[202:205], v174 offset:192
	v_fma_f32 v67, v67, s84, -v199
	v_exp_f32_e32 v67, v67
	v_add_f32_e32 v200, v200, v66
	v_fma_f32 v68, v68, s84, -v199
	s_waitcnt lgkmcnt(5)
	v_mfma_f32_32x32x16_bf16 v[80:95], v[206:209], v[100:103], v[80:95]
	ds_read_b128 v[206:209], v174 offset:224
	v_exp_f32_e32 v68, v68
	v_add_f32_e32 v200, v200, v67
	v_fma_f32 v69, v69, s84, -v199
	v_exp_f32_e32 v69, v69
	s_waitcnt lgkmcnt(5)
	v_mfma_f32_32x32x16_bf16 v[80:95], v[210:213], v[104:107], v[80:95]
	ds_read_b128 v[210:213], v174 offset:256
	v_add_f32_e32 v200, v200, v68
	v_fma_f32 v70, v70, s84, -v199
	v_exp_f32_e32 v70, v70
	v_add_f32_e32 v200, v200, v69
	s_waitcnt lgkmcnt(5)
	v_mfma_f32_32x32x16_bf16 v[80:95], v[214:217], v[108:111], v[80:95]
	ds_read_b128 v[214:217], v174 offset:288
	v_fma_f32 v71, v71, s84, -v199
	v_exp_f32_e32 v71, v71
	v_add_f32_e32 v200, v200, v70
	v_fma_f32 v72, v72, s84, -v199
	s_waitcnt lgkmcnt(5)
	v_mfma_f32_32x32x16_bf16 v[80:95], v[218:221], v[112:115], v[80:95]
	ds_read_b128 v[218:221], v174 offset:320
	v_exp_f32_e32 v72, v72
	v_add_f32_e32 v200, v200, v71
	v_fma_f32 v73, v73, s84, -v199
	v_exp_f32_e32 v73, v73
	s_waitcnt lgkmcnt(5)
	v_mfma_f32_32x32x16_bf16 v[80:95], v[222:225], v[116:119], v[80:95]
	ds_read_b128 v[222:225], v174 offset:352
	v_add_f32_e32 v200, v200, v72
	v_fma_f32 v74, v74, s84, -v199
	v_exp_f32_e32 v74, v74
	v_add_f32_e32 v200, v200, v73
	s_waitcnt lgkmcnt(5)
	v_mfma_f32_32x32x16_bf16 v[80:95], v[202:205], v[120:123], v[80:95]
	ds_read_b128 v[164:167], v173 offset:0
	v_fma_f32 v75, v75, s84, -v199
	v_exp_f32_e32 v75, v75
	v_add_f32_e32 v200, v200, v74
	v_fma_f32 v76, v76, s84, -v199
	s_waitcnt lgkmcnt(5)
	v_mfma_f32_32x32x16_bf16 v[80:95], v[206:209], v[124:127], v[80:95]
	ds_read_b128 v[168:171], v173 offset:4608
	v_exp_f32_e32 v76, v76
	v_add_f32_e32 v200, v200, v75
	v_fma_f32 v77, v77, s84, -v199
	v_exp_f32_e32 v77, v77
	s_waitcnt lgkmcnt(5)
	v_mfma_f32_32x32x16_bf16 v[80:95], v[210:213], v[160:163], v[80:95]
	ds_read_b128 v[176:179], v173 offset:9216
	v_add_f32_e32 v200, v200, v76
	v_fma_f32 v78, v78, s84, -v199
	v_exp_f32_e32 v78, v78
	v_add_f32_e32 v200, v200, v77
	s_waitcnt lgkmcnt(5)
	v_mfma_f32_32x32x16_bf16 v[80:95], v[214:217], v[152:155], v[80:95]
	ds_read_b128 v[226:229], v173 offset:13824
	v_fma_f32 v79, v79, s84, -v199
	v_exp_f32_e32 v79, v79
	v_add_f32_e32 v200, v200, v78
	v_add_f32_e32 v200, v200, v79
	s_waitcnt lgkmcnt(5)
	v_mfma_f32_32x32x16_bf16 v[80:95], v[218:221], v[156:159], v[80:95]
	v_cvt_pk_bf16_f32 v64, v64, v65
	v_cvt_pk_bf16_f32 v65, v66, v67
	v_cvt_pk_bf16_f32 v66, v68, v69
	v_cvt_pk_bf16_f32 v67, v70, v71
	s_waitcnt lgkmcnt(4)
	v_mfma_f32_32x32x16_bf16 v[80:95], v[222:225], v[148:151], v[80:95]
	v_cvt_pk_bf16_f32 v68, v72, v73
	v_cvt_pk_bf16_f32 v69, v74, v75
	v_cvt_pk_bf16_f32 v70, v76, v77
	v_cvt_pk_bf16_f32 v71, v78, v79
	s_waitcnt lgkmcnt(3)
	v_mfma_f32_32x32x16_bf16 v[48:63], v[164:167], v[64:67], v[48:63]
	ds_read_b128 v[164:167], v173 offset:32
	s_waitcnt lgkmcnt(3)
	v_mfma_f32_32x32x16_bf16 v[32:47], v[168:171], v[64:67], v[32:47]
	ds_read_b128 v[168:171], v173 offset:4640
	s_waitcnt lgkmcnt(3)
	v_mfma_f32_32x32x16_bf16 v[16:31], v[176:179], v[64:67], v[16:31]
	ds_read_b128 v[176:179], v173 offset:9248
	s_waitcnt lgkmcnt(3)
	v_mfma_f32_32x32x16_bf16 v[0:15], v[226:229], v[64:67], v[0:15]
	ds_read_b128 v[226:229], v173 offset:13856
	ds_read_b128 v[202:205], v174 offset:12800
	ds_read_b128 v[206:209], v174 offset:12832
	ds_read_b128 v[210:213], v174 offset:12864
	ds_read_b128 v[214:217], v174 offset:12896
	ds_read_b128 v[218:221], v174 offset:12928
	ds_read_b128 v[222:225], v174 offset:12960
	s_cmp_gt_i32 s33, s97
	s_cbranch_scc1 .Lat_mask_a_0

.Lat_resc_b_0_ret:
	s_cmp_lt_i32 s54, s53
	s_cbranch_scc0 .Lat_skip_st_0
	s_add_i32 s4, s54, 1
	s_cmp_lt_i32 s4, s53
	s_cbranch_scc1 .Lat_vm2_0
	s_waitcnt vmcnt(0)
	s_branch .Lat_vmdone_0
.Lat_vm2_0:
	s_waitcnt vmcnt(2)
.Lat_vmdone_0:
	v_add_u32_e32 v235, 0x6400, v194
	ds_write_b128 v235, v[128:131]
	ds_write_b128 v235, v[132:135] offset:12800
	v_add_u32_e32 v235, 0x6400, v184
	ds_write_b128 v235, v[136:139] offset:256
	s_add_i32 s4, s52, 1
	s_cmp_lg_u32 s52, 2
	s_cselect_b32 s4, s4, 0
	s_mul_i32 s4, s4, 0x4800
	v_add_u32_e32 v235, s4, v185
	v_add_u32_e32 v245, 0xc800, v235
	v_add_u32_e32 v235, 0xe800, v235
	ds_write2_b64 v245, v[236:237], v[238:239] offset1:2
	ds_write2_b64 v235, v[240:241], v[242:243] offset0:128 offset1:130
.Lat_skip_st_0:
	s_add_i32 s4, s54, 1
	s_cmp_lt_i32 s4, s53
	s_cbranch_scc0 .Lat_skip_ld_0
	s_add_u32 s20, s20, 0x20000
	s_addc_u32 s21, s21, 0
	s_add_u32 s22, s22, 0x2000
	s_addc_u32 s23, s23, 0
	global_load_dwordx4 v[128:131], v201, s[20:21]
	global_load_dwordx4 v[132:135], v230, s[20:21]
	global_load_dwordx4 v[136:139], v231, s[22:23]
	s_add_i32 s4, s54, 2
	s_cmp_lt_i32 s4, s53
	s_cbranch_scc0 .Lat_skip_ld_0
	s_add_u32 s24, s24, 0x80
	s_addc_u32 s25, s25, 0
	global_load_dwordx4 v[236:239], v232, s[24:25]
	global_load_dwordx4 v[240:243], v233, s[24:25]
.Lat_skip_ld_0:
	s_add_i32 s4, s52, 1
	s_cmp_lg_u32 s52, 2
	s_cselect_b32 s52, s4, 0
	s_add_i32 s33, s33, 64
	v_subrev_u32_e32 v197, 64, v197
	v_add_u32_e32 v173, 0xc840, v234
	s_mov_b32 s0, s54
	s_cmp_eq_u32 s53, s54
	s_waitcnt lgkmcnt(0)
	s_barrier
	s_cbranch_scc1 .Lat_tail
	s_add_i32 s54, s0, 1
	v_add_u32_e32 v174, 0x6400, v196
	s_mul_i32 s4, s52, 0x4800
	v_add_u32_e32 v234, s4, v195
	ds_read_b128 v[202:205], v174 offset:0
	ds_read_b128 v[206:209], v174 offset:32
	ds_read_b128 v[210:213], v174 offset:64
	ds_read_b128 v[214:217], v174 offset:96
	ds_read_b128 v[218:221], v174 offset:128
	ds_read_b128 v[222:225], v174 offset:160
	v_fma_f32 v64, v64, s84, -v199
	v_exp_f32_e32 v64, v64
	v_fma_f32 v65, v65, s84, -v199
	v_exp_f32_e32 v65, v65
	v_add_f32_e32 v200, v200, v64
	v_fma_f32 v66, v66, s84, -v199
	v_exp_f32_e32 v66, v66
	v_add_f32_e32 v200, v200, v65
	s_waitcnt lgkmcnt(5)
	v_mfma_f32_32x32x16_bf16 v[80:95], v[202:205], v[96:99], 0
	ds_read_b128 v[202:205], v174 offset:192
	v_fma_f32 v67, v67, s84, -v199
	v_exp_f32_e32 v67, v67
	v_add_f32_e32 v200, v200, v66
	v_fma_f32 v68, v68, s84, -v199
	s_waitcnt lgkmcnt(5)
	v_mfma_f32_32x32x16_bf16 v[80:95], v[206:209], v[100:103], v[80:95]
	ds_read_b128 v[206:209], v174 offset:224
	v_exp_f32_e32 v68, v68
	v_add_f32_e32 v200, v200, v67
	v_fma_f32 v69, v69, s84, -v199
	v_exp_f32_e32 v69, v69
	s_waitcnt lgkmcnt(5)
	v_mfma_f32_32x32x16_bf16 v[80:95], v[210:213], v[104:107], v[80:95]
	ds_read_b128 v[210:213], v174 offset:256
	v_add_f32_e32 v200, v200, v68
	v_fma_f32 v70, v70, s84, -v199
	v_exp_f32_e32 v70, v70
	v_add_f32_e32 v200, v200, v69
	s_waitcnt lgkmcnt(5)
	v_mfma_f32_32x32x16_bf16 v[80:95], v[214:217], v[108:111], v[80:95]
	ds_read_b128 v[214:217], v174 offset:288
	v_fma_f32 v71, v71, s84, -v199
	v_exp_f32_e32 v71, v71
	v_add_f32_e32 v200, v200, v70
	v_fma_f32 v72, v72, s84, -v199
	s_waitcnt lgkmcnt(5)
	v_mfma_f32_32x32x16_bf16 v[80:95], v[218:221], v[112:115], v[80:95]
	ds_read_b128 v[218:221], v174 offset:320
	v_exp_f32_e32 v72, v72
	v_add_f32_e32 v200, v200, v71
	v_fma_f32 v73, v73, s84, -v199
	v_exp_f32_e32 v73, v73
	s_waitcnt lgkmcnt(5)
	v_mfma_f32_32x32x16_bf16 v[80:95], v[222:225], v[116:119], v[80:95]
	ds_read_b128 v[222:225], v174 offset:352
	v_add_f32_e32 v200, v200, v72
	v_fma_f32 v74, v74, s84, -v199
	v_exp_f32_e32 v74, v74
	v_add_f32_e32 v200, v200, v73
	s_waitcnt lgkmcnt(5)
	v_mfma_f32_32x32x16_bf16 v[80:95], v[202:205], v[120:123], v[80:95]
	ds_read_b128 v[164:167], v173 offset:0
	v_fma_f32 v75, v75, s84, -v199
	v_exp_f32_e32 v75, v75
	v_add_f32_e32 v200, v200, v74
	v_fma_f32 v76, v76, s84, -v199
	s_waitcnt lgkmcnt(5)
	v_mfma_f32_32x32x16_bf16 v[80:95], v[206:209], v[124:127], v[80:95]
	ds_read_b128 v[168:171], v173 offset:4608
	v_exp_f32_e32 v76, v76
	v_add_f32_e32 v200, v200, v75
	v_fma_f32 v77, v77, s84, -v199
	v_exp_f32_e32 v77, v77
	s_waitcnt lgkmcnt(5)
	v_mfma_f32_32x32x16_bf16 v[80:95], v[210:213], v[160:163], v[80:95]
	ds_read_b128 v[176:179], v173 offset:9216
	v_add_f32_e32 v200, v200, v76
	v_fma_f32 v78, v78, s84, -v199
	v_exp_f32_e32 v78, v78
	v_add_f32_e32 v200, v200, v77
	s_waitcnt lgkmcnt(5)
	v_mfma_f32_32x32x16_bf16 v[80:95], v[214:217], v[152:155], v[80:95]
	ds_read_b128 v[226:229], v173 offset:13824
	v_fma_f32 v79, v79, s84, -v199
	v_exp_f32_e32 v79, v79
	v_add_f32_e32 v200, v200, v78
	v_add_f32_e32 v200, v200, v79
	s_waitcnt lgkmcnt(5)
	v_mfma_f32_32x32x16_bf16 v[80:95], v[218:221], v[156:159], v[80:95]
	v_cvt_pk_bf16_f32 v64, v64, v65
	v_cvt_pk_bf16_f32 v65, v66, v67
	v_cvt_pk_bf16_f32 v66, v68, v69
	v_cvt_pk_bf16_f32 v67, v70, v71
	s_waitcnt lgkmcnt(4)
	v_mfma_f32_32x32x16_bf16 v[80:95], v[222:225], v[148:151], v[80:95]
	v_cvt_pk_bf16_f32 v68, v72, v73
	v_cvt_pk_bf16_f32 v69, v74, v75
	v_cvt_pk_bf16_f32 v70, v76, v77
	v_cvt_pk_bf16_f32 v71, v78, v79
	s_waitcnt lgkmcnt(3)
	v_mfma_f32_32x32x16_bf16 v[48:63], v[164:167], v[64:67], v[48:63]
	ds_read_b128 v[164:167], v173 offset:32
	s_waitcnt lgkmcnt(3)
	v_mfma_f32_32x32x16_bf16 v[32:47], v[168:171], v[64:67], v[32:47]
	ds_read_b128 v[168:171], v173 offset:4640
	s_waitcnt lgkmcnt(3)
	v_mfma_f32_32x32x16_bf16 v[16:31], v[176:179], v[64:67], v[16:31]
	ds_read_b128 v[176:179], v173 offset:9248
	s_waitcnt lgkmcnt(3)
	v_mfma_f32_32x32x16_bf16 v[0:15], v[226:229], v[64:67], v[0:15]
	ds_read_b128 v[226:229], v173 offset:13856
	ds_read_b128 v[202:205], v174 offset:12800
	ds_read_b128 v[206:209], v174 offset:12832
	ds_read_b128 v[210:213], v174 offset:12864
	ds_read_b128 v[214:217], v174 offset:12896
	ds_read_b128 v[218:221], v174 offset:12928
	ds_read_b128 v[222:225], v174 offset:12960
	s_cmp_gt_i32 s33, s97
	s_cbranch_scc1 .Lat_mask_a_1

.Lat_vmdone_1:
	v_mov_b32_e32 v235, v194
	ds_write_b128 v235, v[128:131]
	ds_write_b128 v235, v[132:135] offset:12800
	v_mov_b32_e32 v235, v184
	ds_write_b128 v235, v[136:139] offset:256
	s_add_i32 s4, s52, 1
	s_cmp_lg_u32 s52, 2
	s_cselect_b32 s4, s4, 0
	s_mul_i32 s4, s4, 0x4800
	v_add_u32_e32 v235, s4, v185
	v_add_u32_e32 v245, 0xc800, v235
	v_add_u32_e32 v235, 0xe800, v235
	ds_write2_b64 v245, v[140:141], v[142:143] offset1:2
	ds_write2_b64 v235, v[144:145], v[146:147] offset0:128 offset1:130
.Lat_skip_st_1:
	s_add_i32 s4, s54, 1
	s_cmp_lt_i32 s4, s53
	s_cbranch_scc0 .Lat_skip_ld_1
	s_add_u32 s20, s20, 0x20000
	s_addc_u32 s21, s21, 0
	s_add_u32 s22, s22, 0x2000
	s_addc_u32 s23, s23, 0
	global_load_dwordx4 v[128:131], v201, s[20:21]
	global_load_dwordx4 v[132:135], v230, s[20:21]
	global_load_dwordx4 v[136:139], v231, s[22:23]
	s_add_i32 s4, s54, 2
	s_cmp_lt_i32 s4, s53
	s_cbranch_scc0 .Lat_skip_ld_1
	s_add_u32 s24, s24, 0x80
	s_addc_u32 s25, s25, 0
	global_load_dwordx4 v[140:143], v232, s[24:25]
	global_load_dwordx4 v[144:147], v233, s[24:25]

.Lat_tail:
	v_fma_f32 v64, v64, s84, -v199
	v_exp_f32_e32 v64, v64
	v_fma_f32 v65, v65, s84, -v199
	v_exp_f32_e32 v65, v65
	v_add_f32_e32 v200, v200, v64
	v_fma_f32 v66, v66, s84, -v199
	v_exp_f32_e32 v66, v66
	v_add_f32_e32 v200, v200, v65
	v_fma_f32 v67, v67, s84, -v199
	v_exp_f32_e32 v67, v67
	v_add_f32_e32 v200, v200, v66
	v_fma_f32 v68, v68, s84, -v199
	v_exp_f32_e32 v68, v68
	v_add_f32_e32 v200, v200, v67
	v_fma_f32 v69, v69, s84, -v199
	v_exp_f32_e32 v69, v69
	v_add_f32_e32 v200, v200, v68
	v_fma_f32 v70, v70, s84, -v199
	v_exp_f32_e32 v70, v70
	v_add_f32_e32 v200, v200, v69
	v_fma_f32 v71, v71, s84, -v199
	v_exp_f32_e32 v71, v71
	v_add_f32_e32 v200, v200, v70
	v_fma_f32 v72, v72, s84, -v199
	v_exp_f32_e32 v72, v72
	v_add_f32_e32 v200, v200, v71
	v_fma_f32 v73, v73, s84, -v199
	v_exp_f32_e32 v73, v73
	v_add_f32_e32 v200, v200, v72
	v_fma_f32 v74, v74, s84, -v199
	v_exp_f32_e32 v74, v74
	v_add_f32_e32 v200, v200, v73
	v_fma_f32 v75, v75, s84, -v199
	v_exp_f32_e32 v75, v75
	v_add_f32_e32 v200, v200, v74
	v_fma_f32 v76, v76, s84, -v199
	v_exp_f32_e32 v76, v76
	v_add_f32_e32 v200, v200, v75
	v_fma_f32 v77, v77, s84, -v199
	v_exp_f32_e32 v77, v77
	v_add_f32_e32 v200, v200, v76
	v_fma_f32 v78, v78, s84, -v199
	v_exp_f32_e32 v78, v78
	v_add_f32_e32 v200, v200, v77
	v_fma_f32 v79, v79, s84, -v199
	v_exp_f32_e32 v79, v79
	v_add_f32_e32 v200, v200, v78
	v_add_f32_e32 v200, v200, v79
	v_cvt_pk_bf16_f32 v202, v64, v65
	v_cvt_pk_bf16_f32 v203, v66, v67
	v_cvt_pk_bf16_f32 v204, v68, v69
	v_cvt_pk_bf16_f32 v205, v70, v71
	v_cvt_pk_bf16_f32 v206, v72, v73
	v_cvt_pk_bf16_f32 v207, v74, v75
	v_cvt_pk_bf16_f32 v208, v76, v77
	v_cvt_pk_bf16_f32 v209, v78, v79
	v_mov_b32_e32 v68, v202
	v_mov_b32_e32 v69, v203
	v_mov_b32_e32 v70, v204
	v_mov_b32_e32 v71, v205
	v_mov_b32_e32 v64, v206
	v_mov_b32_e32 v65, v207
	v_mov_b32_e32 v66, v208
	v_mov_b32_e32 v67, v209
	s_branch .LBB0_1332

.Lat_resc_b_0:
	ds_bpermute_b32 v175, v246, v172
	s_waitcnt lgkmcnt(0)
	v_max3_f32 v175, v199, v172, v175
	v_sub_f32_e32 v172, v199, v175
	v_exp_f32_e32 v172, v172
	v_mov_b32_e32 v199, v175
	s_nop 0
	v_mul_f32_e32 v200, v200, v172
	s_nop 15
	s_nop 3
	v_mul_f32_e32 v0, v172, v0
	v_mul_f32_e32 v1, v172, v1
	v_mul_f32_e32 v2, v172, v2
	v_mul_f32_e32 v3, v172, v3
	v_mul_f32_e32 v4, v172, v4
	v_mul_f32_e32 v5, v172, v5
	v_mul_f32_e32 v6, v172, v6
	v_mul_f32_e32 v7, v172, v7
	v_mul_f32_e32 v8, v172, v8
	v_mul_f32_e32 v9, v172, v9
	v_mul_f32_e32 v10, v172, v10
	v_mul_f32_e32 v11, v172, v11
	v_mul_f32_e32 v12, v172, v12
	v_mul_f32_e32 v13, v172, v13
	v_mul_f32_e32 v14, v172, v14
	v_mul_f32_e32 v15, v172, v15
	v_mul_f32_e32 v16, v172, v16
	v_mul_f32_e32 v17, v172, v17
	v_mul_f32_e32 v18, v172, v18
	v_mul_f32_e32 v19, v172, v19
	v_mul_f32_e32 v20, v172, v20
	v_mul_f32_e32 v21, v172, v21
	v_mul_f32_e32 v22, v172, v22
	v_mul_f32_e32 v23, v172, v23
	v_mul_f32_e32 v24, v172, v24
	v_mul_f32_e32 v25, v172, v25
	v_mul_f32_e32 v26, v172, v26
	v_mul_f32_e32 v27, v172, v27
	v_mul_f32_e32 v28, v172, v28
	v_mul_f32_e32 v29, v172, v29
	v_mul_f32_e32 v30, v172, v30
	v_mul_f32_e32 v31, v172, v31
	v_mul_f32_e32 v32, v172, v32
	v_mul_f32_e32 v33, v172, v33
	v_mul_f32_e32 v34, v172, v34
	v_mul_f32_e32 v35, v172, v35
	v_mul_f32_e32 v36, v172, v36
	v_mul_f32_e32 v37, v172, v37
	v_mul_f32_e32 v38, v172, v38
	v_mul_f32_e32 v39, v172, v39
	v_mul_f32_e32 v40, v172, v40
	v_mul_f32_e32 v41, v172, v41
	v_mul_f32_e32 v42, v172, v42
	v_mul_f32_e32 v43, v172, v43
	v_mul_f32_e32 v44, v172, v44
	v_mul_f32_e32 v45, v172, v45
	v_mul_f32_e32 v46, v172, v46
	v_mul_f32_e32 v47, v172, v47
	v_mul_f32_e32 v48, v172, v48
	v_mul_f32_e32 v49, v172, v49
	v_mul_f32_e32 v50, v172, v50
	v_mul_f32_e32 v51, v172, v51
	v_mul_f32_e32 v52, v172, v52
	v_mul_f32_e32 v53, v172, v53
	v_mul_f32_e32 v54, v172, v54
	v_mul_f32_e32 v55, v172, v55
	v_mul_f32_e32 v56, v172, v56
	v_mul_f32_e32 v57, v172, v57
	v_mul_f32_e32 v58, v172, v58
	v_mul_f32_e32 v59, v172, v59
	v_mul_f32_e32 v60, v172, v60
	v_mul_f32_e32 v61, v172, v61
	v_mul_f32_e32 v62, v172, v62
	v_mul_f32_e32 v63, v172, v63
	s_branch .Lat_resc_b_0_ret
.Lat_mask_a_1:
	s_nop 7
	v_cmp_gt_i32_e64 s[4:5], 0, v197
	v_cmp_gt_i32_e64 s[6:7], 1, v197
	v_cmp_gt_i32_e64 s[8:9], 2, v197
	v_cmp_gt_i32_e64 s[10:11], 3, v197
	v_cmp_gt_i32_e64 s[12:13], 8, v197
	v_cmp_gt_i32_e64 s[14:15], 9, v197
	v_cmp_gt_i32_e64 s[16:17], 10, v197
	v_cmp_gt_i32_e64 s[18:19], 11, v197
	v_cndmask_b32_e64 v80, v80, v192, s[4:5]
	v_cndmask_b32_e64 v81, v81, v192, s[6:7]
	v_cndmask_b32_e64 v82, v82, v192, s[8:9]
	v_cndmask_b32_e64 v83, v83, v192, s[10:11]
	v_cndmask_b32_e64 v84, v84, v192, s[12:13]
	v_cndmask_b32_e64 v85, v85, v192, s[14:15]
	v_cndmask_b32_e64 v86, v86, v192, s[16:17]
	v_cndmask_b32_e64 v87, v87, v192, s[18:19]
	v_cmp_gt_i32_e64 s[4:5], 16, v197
	v_cmp_gt_i32_e64 s[6:7], 17, v197
	v_cmp_gt_i32_e64 s[8:9], 18, v197
	v_cmp_gt_i32_e64 s[10:11], 19, v197
	v_cmp_gt_i32_e64 s[12:13], 24, v197
	v_cmp_gt_i32_e64 s[14:15], 25, v197
	v_cmp_gt_i32_e64 s[16:17], 26, v197
	v_cmp_gt_i32_e64 s[18:19], 27, v197
	v_cndmask_b32_e64 v88, v88, v192, s[4:5]
	v_cndmask_b32_e64 v89, v89, v192, s[6:7]
	v_cndmask_b32_e64 v90, v90, v192, s[8:9]
	v_cndmask_b32_e64 v91, v91, v192, s[10:11]
	v_cndmask_b32_e64 v92, v92, v192, s[12:13]
	v_cndmask_b32_e64 v93, v93, v192, s[14:15]
	v_cndmask_b32_e64 v94, v94, v192, s[16:17]
	v_cndmask_b32_e64 v95, v95, v192, s[18:19]
	s_branch .Lat_mask_a_1_ret
